# GU and in-proj K-loops: on the tile's last K iteration touch the four 128-B ssq lines (memory-side atomics, so L2-cold) that the epilogue reads
# baseline (speedup 1.0000x reference)
; #define PG8_STAGE(bufoff, gbase, voff) do { _Pragma("unroll") for (int _i = 0; _i < 2; ++_i) \
;         __builtin_amdgcn_global_load_lds((const unsigned*)((const char*)(gbase) + (voff)[_i]), (PG8_LAS unsigned*)(lds + (bufoff) + ldsw + _i * 8192), 16, 0, 0); } while (0)
; #define PG8_LDA(dst, b, h) do { _Pragma("unroll") for (int m = 0; m < 4; ++m) _Pragma("unroll") for (int k = 0; k < 2; ++k) dst[m][k] = *(const PG8_LAS bf16x8*)(lds + PG8_SA(b, h) + aoff + m * 2048 + k * 1024); } while (0)
; #define PG8_LDB(dst, b, h) do { _Pragma("unroll") for (int n = 0; n < 2; ++n) _Pragma("unroll") for (int k = 0; k < 2; ++k) dst[n][k] = *(const PG8_LAS bf16x8*)(lds + PG8_SB(b, h) + boff + n * 2048 + k * 1024); } while (0)
; #define PG8_MMA(ai, bj, At, Bt) do { __builtin_amdgcn_s_setprio(1); _Pragma("unroll") for (int m = 0; m < 4; ++m) _Pragma("unroll") for (int n = 0; n < 2; ++n) _Pragma("unroll") for (int k = 0; k < 2; ++k) \
;         acc[ai][bj][m][n] = __builtin_amdgcn_mfma_f32_16x16x32_bf16(Bt[n][k], At[m][k], acc[ai][bj][m][n], 0, 0, 0); __builtin_amdgcn_s_setprio(0); } while (0)
; #define PG8_WAIT_V(n) asm volatile("s_waitcnt vmcnt(" #n ")" ::: "memory")
; #define PG8_WAIT_L(n) asm volatile("s_waitcnt lgkmcnt(" #n ")" ::: "memory")
; #define PG8_BAR __builtin_amdgcn_s_barrier()
; #define PG8_SCHED __builtin_amdgcn_sched_barrier(0)
; template <class Epi, class Sched, bool ALIGN_EPI = false, bool SP2 = false, bool ATILED = false, bool BTILED = false>
; __device__ __forceinline__ void gemm_phase(PG8_LAS unsigned char* lds, const Gemm g, const Sched& S, const Epi& E, const int tid) {
;     ...
;             PG8_LDB(B0, 0, 0); PG8_LDB(B1, 0, 1); PG8_SCHED; PG8_LDA(At, 0, 0); PG8_STAGE(PG8_SA(1, 1), a1 + hstepA, voffA);
;             PG8_WAIT_V(8); PG8_WAIT_L(0); PG8_BAR; PG8_MMA(0, 0, At, B0); PG8_MMA(0, 1, At, B1); PG8_BAR; PG8_SCHED;
;             PG8_LDA(At, 0, 1); PG8_STAGE(PG8_SB(0, 0), b2, voffB); PG8_STAGE(PG8_SB(0, 1), b2 + hstepB, voffB); PG8_STAGE(PG8_SA(0, 0), a2, voffA);
;             PG8_WAIT_V(8); PG8_WAIT_L(0); PG8_BAR; PG8_MMA(1, 0, At, B0); PG8_MMA(1, 1, At, B1); PG8_BAR; PG8_SCHED;
.LBB0_166:
	s_add_u32 s54, s52, 0x4000
	s_addc_u32 s55, s53, 0
	s_cmp_eq_u32 s76, 12
	s_cselect_b32 s58, s19, s54
	s_cselect_b32 s59, s15, s55
	s_cselect_b32 s56, s29, s74
	s_cselect_b32 s57, s13, s75
	s_add_u32 s54, s58, 0x8000
	s_addc_u32 s55, s59, 0
	s_add_i32 s77, 0, 0x10000
	s_add_i32 s80, 0, 0x14000
	v_add_u32_e32 v82, s77, v1
	v_add_u32_e32 v195, s80, v1
	ds_read_b128 v[66:69], v82
	ds_read_b128 v[70:73], v82 offset:1024
	ds_read_b128 v[78:81], v82 offset:2048
	ds_read_b128 v[82:85], v82 offset:3072
	ds_read_b128 v[180:183], v195
	ds_read_b128 v[186:189], v195 offset:1024
	ds_read_b128 v[190:193], v195 offset:2048
	ds_read_b128 v[196:199], v195 offset:3072
	v_lshl_add_u64 v[228:229], s[52:53], 0, v[174:175]
	s_add_i32 m0, s66, 0xc000
	ds_read_b128 v[200:203], v155
	ds_read_b128 v[204:207], v155 offset:1024
	ds_read_b128 v[208:211], v155 offset:2048
	ds_read_b128 v[212:215], v155 offset:3072
	ds_read_b128 v[216:219], v155 offset:4096
	ds_read_b128 v[220:223], v155 offset:5120
	ds_read_b128 v[224:227], v155 offset:6144
	ds_read_b128 v[242:245], v155 offset:7168
	global_load_lds_dwordx4 v[228:229], off
	v_lshl_add_u64 v[228:229], s[52:53], 0, v[176:177]
	s_add_i32 m0, s66, 0xe000
	s_nop 0
	global_load_lds_dwordx4 v[228:229], off
	s_waitcnt vmcnt(8)
	s_waitcnt lgkmcnt(0)
	s_barrier
	s_setprio 1
	s_waitcnt lgkmcnt(0)
	v_mfma_f32_16x16x32_bf16 v[142:145], v[66:69], v[200:203], v[142:145]
	v_mfma_f32_16x16x32_bf16 v[138:141], v[78:81], v[200:203], v[138:141]
	v_mfma_f32_16x16x32_bf16 v[126:129], v[66:69], v[208:211], v[126:129]
	v_mfma_f32_16x16x32_bf16 v[118:121], v[78:81], v[208:211], v[118:121]
	v_mfma_f32_16x16x32_bf16 v[110:113], v[66:69], v[216:219], v[110:113]
	v_mfma_f32_16x16x32_bf16 v[102:105], v[78:81], v[216:219], v[102:105]
	v_mfma_f32_16x16x32_bf16 v[94:97], v[66:69], v[224:227], v[94:97]
	v_mfma_f32_16x16x32_bf16 v[86:89], v[78:81], v[224:227], v[86:89]
	v_mfma_f32_16x16x32_bf16 v[142:145], v[70:73], v[204:207], v[142:145]
	v_mfma_f32_16x16x32_bf16 v[138:141], v[82:85], v[204:207], v[138:141]
	v_mfma_f32_16x16x32_bf16 v[126:129], v[70:73], v[212:215], v[126:129]
	v_mfma_f32_16x16x32_bf16 v[118:121], v[82:85], v[212:215], v[118:121]
	v_mfma_f32_16x16x32_bf16 v[110:113], v[70:73], v[220:223], v[110:113]
	v_mfma_f32_16x16x32_bf16 v[102:105], v[82:85], v[220:223], v[102:105]
	v_mfma_f32_16x16x32_bf16 v[94:97], v[70:73], v[242:245], v[94:97]
	v_mfma_f32_16x16x32_bf16 v[86:89], v[82:85], v[242:245], v[86:89]
	s_setprio 0
	s_setprio 1
	v_mfma_f32_16x16x32_bf16 v[134:137], v[180:183], v[200:203], v[134:137]
	v_mfma_f32_16x16x32_bf16 v[130:133], v[190:193], v[200:203], v[130:133]
	v_mfma_f32_16x16x32_bf16 v[122:125], v[180:183], v[208:211], v[122:125]
	v_mfma_f32_16x16x32_bf16 v[114:117], v[190:193], v[208:211], v[114:117]
	v_mfma_f32_16x16x32_bf16 v[106:109], v[180:183], v[216:219], v[106:109]
	v_mfma_f32_16x16x32_bf16 v[98:101], v[190:193], v[216:219], v[98:101]
	v_mfma_f32_16x16x32_bf16 v[90:93], v[180:183], v[224:227], v[90:93]
	v_mfma_f32_16x16x32_bf16 v[74:77], v[190:193], v[224:227], v[74:77]
	v_mfma_f32_16x16x32_bf16 v[134:137], v[186:189], v[204:207], v[134:137]
	v_mfma_f32_16x16x32_bf16 v[130:133], v[196:199], v[204:207], v[130:133]
	v_mfma_f32_16x16x32_bf16 v[122:125], v[186:189], v[212:215], v[122:125]
	v_mfma_f32_16x16x32_bf16 v[114:117], v[196:199], v[212:215], v[114:117]
	v_mfma_f32_16x16x32_bf16 v[106:109], v[186:189], v[220:223], v[106:109]
	v_mfma_f32_16x16x32_bf16 v[98:101], v[196:199], v[220:223], v[98:101]
	v_mfma_f32_16x16x32_bf16 v[90:93], v[186:189], v[242:245], v[90:93]
	v_mfma_f32_16x16x32_bf16 v[74:77], v[196:199], v[242:245], v[74:77]
	s_setprio 0
	s_barrier
	s_add_i32 s77, s77, s64
	v_lshl_add_u64 v[228:229], s[56:57], 0, v[150:151]
	s_mov_b32 m0, s77
	ds_read_b128 v[200:203], v155 offset:16384
	ds_read_b128 v[204:207], v155 offset:17408
	ds_read_b128 v[208:211], v155 offset:18432
	ds_read_b128 v[212:215], v155 offset:19456
	ds_read_b128 v[216:219], v155 offset:20480
	ds_read_b128 v[220:223], v155 offset:21504
	ds_read_b128 v[224:227], v155 offset:22528
	ds_read_b128 v[242:245], v155 offset:23552
	global_load_lds_dwordx4 v[228:229], off
	s_add_i32 m0, s77, 0x2000
	s_add_u32 s78, s56, 0x4000
	v_lshl_add_u64 v[228:229], s[56:57], 0, v[146:147]
	s_addc_u32 s79, s57, 0
	s_add_i32 s77, s80, s64
	global_load_lds_dwordx4 v[228:229], off
	v_lshl_add_u64 v[228:229], s[78:79], 0, v[150:151]
	s_mov_b32 m0, s77
	s_nop 0
	global_load_lds_dwordx4 v[228:229], off
	v_lshl_add_u64 v[228:229], s[78:79], 0, v[146:147]
	s_add_i32 m0, s77, 0x2000
	s_nop 0
	global_load_lds_dwordx4 v[228:229], off
	v_lshl_add_u64 v[228:229], s[58:59], 0, v[152:153]
	s_mov_b32 m0, s66
	s_nop 0
	global_load_lds_dwordx4 v[228:229], off
	v_lshl_add_u64 v[228:229], s[58:59], 0, v[148:149]
	s_mov_b32 m0, s67
	s_nop 0
	global_load_lds_dwordx4 v[228:229], off
	s_waitcnt vmcnt(8)
	s_waitcnt lgkmcnt(0)
	s_barrier
; #define PG8_STAGE(bufoff, gbase, voff) do { _Pragma("unroll") for (int _i = 0; _i < 2; ++_i) \
;         __builtin_amdgcn_global_load_lds((const unsigned*)((const char*)(gbase) + (voff)[_i]), (PG8_LAS unsigned*)(lds + (bufoff) + ldsw + _i * 8192), 16, 0, 0); } while (0)
; #define PG8_LDA(dst, b, h) do { _Pragma("unroll") for (int m = 0; m < 4; ++m) _Pragma("unroll") for (int k = 0; k < 2; ++k) dst[m][k] = *(const PG8_LAS bf16x8*)(lds + PG8_SA(b, h) + aoff + m * 2048 + k * 1024); } while (0)
; #define PG8_LDB(dst, b, h) do { _Pragma("unroll") for (int n = 0; n < 2; ++n) _Pragma("unroll") for (int k = 0; k < 2; ++k) dst[n][k] = *(const PG8_LAS bf16x8*)(lds + PG8_SB(b, h) + boff + n * 2048 + k * 1024); } while (0)
; #define PG8_MMA(ai, bj, At, Bt) do { __builtin_amdgcn_s_setprio(1); _Pragma("unroll") for (int m = 0; m < 4; ++m) _Pragma("unroll") for (int n = 0; n < 2; ++n) _Pragma("unroll") for (int k = 0; k < 2; ++k) \
;         acc[ai][bj][m][n] = __builtin_amdgcn_mfma_f32_16x16x32_bf16(Bt[n][k], At[m][k], acc[ai][bj][m][n], 0, 0, 0); __builtin_amdgcn_s_setprio(0); } while (0)
; #define PG8_WAIT_V(n) asm volatile("s_waitcnt vmcnt(" #n ")" ::: "memory")
; #define PG8_WAIT_L(n) asm volatile("s_waitcnt lgkmcnt(" #n ")" ::: "memory")
; #define PG8_BAR __builtin_amdgcn_s_barrier()
; #define PG8_SCHED __builtin_amdgcn_sched_barrier(0)
; template <class Epi, class Sched, bool ALIGN_EPI = false, bool SP2 = false, bool ATILED = false, bool BTILED = false>
; __device__ __forceinline__ void gemm_phase(PG8_LAS unsigned char* lds, const Gemm g, const Sched& S, const Epi& E, const int tid) {
;     ...
;             PG8_WAIT_V(8); PG8_WAIT_L(0); PG8_BAR; PG8_MMA(1, 0, At, B0); PG8_MMA(1, 1, At, B1); PG8_BAR; PG8_SCHED;
;             PG8_LDB(B0, 1, 0); PG8_LDB(B1, 1, 1); PG8_SCHED; PG8_LDA(At, 1, 0); PG8_STAGE(PG8_SA(0, 1), a2 + hstepA, voffA);
;             PG8_WAIT_V(8); PG8_WAIT_L(0); PG8_BAR; PG8_MMA(0, 0, At, B0); PG8_MMA(0, 1, At, B1); PG8_BAR; PG8_SCHED;
	s_setprio 1
	s_waitcnt lgkmcnt(0)
	v_mfma_f32_16x16x32_bf16 v[62:65], v[66:69], v[200:203], v[62:65]
	v_mfma_f32_16x16x32_bf16 v[54:57], v[78:81], v[200:203], v[54:57]
	v_mfma_f32_16x16x32_bf16 v[46:49], v[66:69], v[208:211], v[46:49]
	v_mfma_f32_16x16x32_bf16 v[38:41], v[78:81], v[208:211], v[38:41]
	v_mfma_f32_16x16x32_bf16 v[30:33], v[66:69], v[216:219], v[30:33]
	v_mfma_f32_16x16x32_bf16 v[22:25], v[78:81], v[216:219], v[22:25]
	v_mfma_f32_16x16x32_bf16 v[14:17], v[66:69], v[224:227], v[14:17]
	v_mfma_f32_16x16x32_bf16 v[6:9], v[78:81], v[224:227], v[6:9]
	v_mfma_f32_16x16x32_bf16 v[62:65], v[70:73], v[204:207], v[62:65]
	v_mfma_f32_16x16x32_bf16 v[54:57], v[82:85], v[204:207], v[54:57]
	v_mfma_f32_16x16x32_bf16 v[46:49], v[70:73], v[212:215], v[46:49]
	v_mfma_f32_16x16x32_bf16 v[38:41], v[82:85], v[212:215], v[38:41]
	v_mfma_f32_16x16x32_bf16 v[30:33], v[70:73], v[220:223], v[30:33]
	v_mfma_f32_16x16x32_bf16 v[22:25], v[82:85], v[220:223], v[22:25]
	v_mfma_f32_16x16x32_bf16 v[14:17], v[70:73], v[242:245], v[14:17]
	v_mfma_f32_16x16x32_bf16 v[6:9], v[82:85], v[242:245], v[6:9]
	s_setprio 0
	s_setprio 1
	v_mfma_f32_16x16x32_bf16 v[58:61], v[180:183], v[200:203], v[58:61]
	v_mfma_f32_16x16x32_bf16 v[50:53], v[190:193], v[200:203], v[50:53]
	v_mfma_f32_16x16x32_bf16 v[42:45], v[180:183], v[208:211], v[42:45]
	v_mfma_f32_16x16x32_bf16 v[34:37], v[190:193], v[208:211], v[34:37]
	v_mfma_f32_16x16x32_bf16 v[26:29], v[180:183], v[216:219], v[26:29]
	v_mfma_f32_16x16x32_bf16 v[18:21], v[190:193], v[216:219], v[18:21]
	v_mfma_f32_16x16x32_bf16 v[10:13], v[180:183], v[224:227], v[10:13]
	v_mfma_f32_16x16x32_bf16 v[2:5], v[190:193], v[224:227], v[2:5]
	v_mfma_f32_16x16x32_bf16 v[58:61], v[186:189], v[204:207], v[58:61]
	v_mfma_f32_16x16x32_bf16 v[50:53], v[196:199], v[204:207], v[50:53]
	v_mfma_f32_16x16x32_bf16 v[42:45], v[186:189], v[212:215], v[42:45]
	v_mfma_f32_16x16x32_bf16 v[34:37], v[196:199], v[212:215], v[34:37]
	v_mfma_f32_16x16x32_bf16 v[26:29], v[186:189], v[220:223], v[26:29]
	v_mfma_f32_16x16x32_bf16 v[18:21], v[196:199], v[220:223], v[18:21]
	v_mfma_f32_16x16x32_bf16 v[10:13], v[186:189], v[242:245], v[10:13]
	v_mfma_f32_16x16x32_bf16 v[2:5], v[196:199], v[242:245], v[2:5]
	s_setprio 0
	s_barrier
	s_add_i32 s77, 0, 0x18000
	s_add_i32 s78, 0, 0x1c000
	v_add_u32_e32 v82, s77, v1
	v_add_u32_e32 v195, s78, v1
	ds_read_b128 v[66:69], v82
	ds_read_b128 v[70:73], v82 offset:1024
	ds_read_b128 v[78:81], v82 offset:2048
	ds_read_b128 v[82:85], v82 offset:3072
	ds_read_b128 v[180:183], v195
	ds_read_b128 v[186:189], v195 offset:1024
	ds_read_b128 v[190:193], v195 offset:2048
	ds_read_b128 v[196:199], v195 offset:3072
	s_add_u32 s58, s58, 0x4000
	s_addc_u32 s59, s59, 0
	s_mov_b32 m0, s68
	v_lshl_add_u64 v[228:229], s[58:59], 0, v[152:153]
	ds_read_b128 v[200:203], v155 offset:32768
	ds_read_b128 v[204:207], v155 offset:33792
	ds_read_b128 v[208:211], v155 offset:34816
	ds_read_b128 v[212:215], v155 offset:35840
	ds_read_b128 v[216:219], v155 offset:36864
	ds_read_b128 v[220:223], v155 offset:37888
	ds_read_b128 v[224:227], v155 offset:38912
	ds_read_b128 v[242:245], v155 offset:39936
	global_load_lds_dwordx4 v[228:229], off
	v_lshl_add_u64 v[228:229], s[58:59], 0, v[148:149]
	s_mov_b32 m0, s69
	s_nop 0
	global_load_lds_dwordx4 v[228:229], off
	s_waitcnt vmcnt(8)
	s_waitcnt lgkmcnt(0)
	s_barrier
	s_setprio 1
	s_waitcnt lgkmcnt(0)
	v_mfma_f32_16x16x32_bf16 v[142:145], v[66:69], v[200:203], v[142:145]
	v_mfma_f32_16x16x32_bf16 v[138:141], v[78:81], v[200:203], v[138:141]
	v_mfma_f32_16x16x32_bf16 v[126:129], v[66:69], v[208:211], v[126:129]
	v_mfma_f32_16x16x32_bf16 v[118:121], v[78:81], v[208:211], v[118:121]
	v_mfma_f32_16x16x32_bf16 v[110:113], v[66:69], v[216:219], v[110:113]
	v_mfma_f32_16x16x32_bf16 v[102:105], v[78:81], v[216:219], v[102:105]
	v_mfma_f32_16x16x32_bf16 v[94:97], v[66:69], v[224:227], v[94:97]
	v_mfma_f32_16x16x32_bf16 v[86:89], v[78:81], v[224:227], v[86:89]
	v_mfma_f32_16x16x32_bf16 v[142:145], v[70:73], v[204:207], v[142:145]
	v_mfma_f32_16x16x32_bf16 v[138:141], v[82:85], v[204:207], v[138:141]
	v_mfma_f32_16x16x32_bf16 v[126:129], v[70:73], v[212:215], v[126:129]
	v_mfma_f32_16x16x32_bf16 v[118:121], v[82:85], v[212:215], v[118:121]
	v_mfma_f32_16x16x32_bf16 v[110:113], v[70:73], v[220:223], v[110:113]
	v_mfma_f32_16x16x32_bf16 v[102:105], v[82:85], v[220:223], v[102:105]
	v_mfma_f32_16x16x32_bf16 v[94:97], v[70:73], v[242:245], v[94:97]
	v_mfma_f32_16x16x32_bf16 v[86:89], v[82:85], v[242:245], v[86:89]
	s_setprio 0
	s_setprio 1
	v_mfma_f32_16x16x32_bf16 v[134:137], v[180:183], v[200:203], v[134:137]
	v_mfma_f32_16x16x32_bf16 v[130:133], v[190:193], v[200:203], v[130:133]
	v_mfma_f32_16x16x32_bf16 v[122:125], v[180:183], v[208:211], v[122:125]
	v_mfma_f32_16x16x32_bf16 v[114:117], v[190:193], v[208:211], v[114:117]
	v_mfma_f32_16x16x32_bf16 v[106:109], v[180:183], v[216:219], v[106:109]
	v_mfma_f32_16x16x32_bf16 v[98:101], v[190:193], v[216:219], v[98:101]
	v_mfma_f32_16x16x32_bf16 v[90:93], v[180:183], v[224:227], v[90:93]
	v_mfma_f32_16x16x32_bf16 v[74:77], v[190:193], v[224:227], v[74:77]
	v_mfma_f32_16x16x32_bf16 v[134:137], v[186:189], v[204:207], v[134:137]
	v_mfma_f32_16x16x32_bf16 v[130:133], v[196:199], v[204:207], v[130:133]
	v_mfma_f32_16x16x32_bf16 v[122:125], v[186:189], v[212:215], v[122:125]
	v_mfma_f32_16x16x32_bf16 v[114:117], v[196:199], v[212:215], v[114:117]
	v_mfma_f32_16x16x32_bf16 v[106:109], v[186:189], v[220:223], v[106:109]
	v_mfma_f32_16x16x32_bf16 v[98:101], v[196:199], v[220:223], v[98:101]
	v_mfma_f32_16x16x32_bf16 v[90:93], v[186:189], v[242:245], v[90:93]
	v_mfma_f32_16x16x32_bf16 v[74:77], v[196:199], v[242:245], v[74:77]
	s_setprio 0
	s_barrier
; #define PG8_STAGE(bufoff, gbase, voff) do { _Pragma("unroll") for (int _i = 0; _i < 2; ++_i) \
;         __builtin_amdgcn_global_load_lds((const unsigned*)((const char*)(gbase) + (voff)[_i]), (PG8_LAS unsigned*)(lds + (bufoff) + ldsw + _i * 8192), 16, 0, 0); } while (0)
; #define PG8_LDA(dst, b, h) do { _Pragma("unroll") for (int m = 0; m < 4; ++m) _Pragma("unroll") for (int k = 0; k < 2; ++k) dst[m][k] = *(const PG8_LAS bf16x8*)(lds + PG8_SA(b, h) + aoff + m * 2048 + k * 1024); } while (0)
; #define PG8_MMA(ai, bj, At, Bt) do { __builtin_amdgcn_s_setprio(1); _Pragma("unroll") for (int m = 0; m < 4; ++m) _Pragma("unroll") for (int n = 0; n < 2; ++n) _Pragma("unroll") for (int k = 0; k < 2; ++k) \
;         acc[ai][bj][m][n] = __builtin_amdgcn_mfma_f32_16x16x32_bf16(Bt[n][k], At[m][k], acc[ai][bj][m][n], 0, 0, 0); __builtin_amdgcn_s_setprio(0); } while (0)
; #define PG8_WAIT_V(n) asm volatile("s_waitcnt vmcnt(" #n ")" ::: "memory")
; #define PG8_WAIT_L(n) asm volatile("s_waitcnt lgkmcnt(" #n ")" ::: "memory")
; #define PG8_BAR __builtin_amdgcn_s_barrier()
; #define PG8_SCHED __builtin_amdgcn_sched_barrier(0)
; template <class Epi, class Sched, bool ALIGN_EPI = false, bool SP2 = false, bool ATILED = false, bool BTILED = false>
; __device__ __forceinline__ void gemm_phase(PG8_LAS unsigned char* lds, const Gemm g, const Sched& S, const Epi& E, const int tid) {
;     ...
;             PG8_LDA(At, 1, 1); PG8_STAGE(PG8_SB(1, 0), b3, voffB); PG8_STAGE(PG8_SB(1, 1), b3 + hstepB, voffB); PG8_STAGE(PG8_SA(1, 0), a3, voffA);
;             PG8_WAIT_V(8); PG8_WAIT_L(0); PG8_BAR; PG8_MMA(1, 0, At, B0); PG8_MMA(1, 1, At, B1); PG8_BAR; PG8_SCHED;
;     __device__ __forceinline__ void operator()(const f32x4 (&acc)[2][2][4][2], const pg8::Unit& u, int wr, int wc, int fr, int fq) const {
;     ...
;         for (int ai = 0; ai < 2; ++ai)
; #pragma unroll
;             for (int m = 0; m < 4; ++m) rs[ai][m] = (float)ssq[row0 + 128 * ai + 16 * m] * (1.0f / 1024.0f);
	s_add_u32 s58, s56, 0x8000
	s_addc_u32 s59, s57, 0
	s_add_i32 s77, s77, s64
	v_lshl_add_u64 v[228:229], s[58:59], 0, v[150:151]
	s_mov_b32 m0, s77
	ds_read_b128 v[200:203], v155 offset:49152
	ds_read_b128 v[204:207], v155 offset:50176
	ds_read_b128 v[208:211], v155 offset:51200
	ds_read_b128 v[212:215], v155 offset:52224
	ds_read_b128 v[216:219], v155 offset:53248
	ds_read_b128 v[220:223], v155 offset:54272
	ds_read_b128 v[224:227], v155 offset:55296
	ds_read_b128 v[242:245], v155 offset:56320
	global_load_lds_dwordx4 v[228:229], off
	s_add_i32 m0, s77, 0x2000
	s_add_u32 s56, s56, 0xc000
	v_lshl_add_u64 v[228:229], s[58:59], 0, v[146:147]
	s_addc_u32 s57, s57, 0
	s_add_i32 s58, s78, s64
	global_load_lds_dwordx4 v[228:229], off
	v_lshl_add_u64 v[228:229], s[56:57], 0, v[150:151]
	s_mov_b32 m0, s58
	s_nop 0
	global_load_lds_dwordx4 v[228:229], off
	v_lshl_add_u64 v[228:229], s[56:57], 0, v[146:147]
	s_add_i32 m0, s58, 0x2000
	s_nop 0
	global_load_lds_dwordx4 v[228:229], off
	v_lshl_add_u64 v[228:229], s[54:55], 0, v[152:153]
	s_mov_b32 m0, s70
	s_nop 0
	global_load_lds_dwordx4 v[228:229], off
	v_lshl_add_u64 v[228:229], s[54:55], 0, v[148:149]
	s_mov_b32 m0, s71
	s_nop 0
	global_load_lds_dwordx4 v[228:229], off
	s_waitcnt vmcnt(8)
	s_cmp_lg_u32 s76, 12
	s_cbranch_scc1 .Lgu_touch_skip
	v_lshl_add_u32 v253, s28, 8, v154
	v_lshlrev_b32_e32 v253, 2, v253
	global_load_dword v252, v253, s[4:5]
	global_load_dword v252, v253, s[4:5] offset:128
	global_load_dword v252, v253, s[4:5] offset:512
	global_load_dword v252, v253, s[4:5] offset:640
.Lgu_touch_skip:
	s_waitcnt lgkmcnt(0)
	s_barrier
	s_setprio 1
	s_waitcnt lgkmcnt(0)
	v_mfma_f32_16x16x32_bf16 v[62:65], v[66:69], v[200:203], v[62:65]
	v_mfma_f32_16x16x32_bf16 v[54:57], v[78:81], v[200:203], v[54:57]
	v_mfma_f32_16x16x32_bf16 v[46:49], v[66:69], v[208:211], v[46:49]
	v_mfma_f32_16x16x32_bf16 v[38:41], v[78:81], v[208:211], v[38:41]
	v_mfma_f32_16x16x32_bf16 v[30:33], v[66:69], v[216:219], v[30:33]
	v_mfma_f32_16x16x32_bf16 v[22:25], v[78:81], v[216:219], v[22:25]
	v_mfma_f32_16x16x32_bf16 v[14:17], v[66:69], v[224:227], v[14:17]
	v_mfma_f32_16x16x32_bf16 v[6:9], v[78:81], v[224:227], v[6:9]
	v_mfma_f32_16x16x32_bf16 v[62:65], v[70:73], v[204:207], v[62:65]
	v_mfma_f32_16x16x32_bf16 v[54:57], v[82:85], v[204:207], v[54:57]
	v_mfma_f32_16x16x32_bf16 v[46:49], v[70:73], v[212:215], v[46:49]
	v_mfma_f32_16x16x32_bf16 v[38:41], v[82:85], v[212:215], v[38:41]
	v_mfma_f32_16x16x32_bf16 v[30:33], v[70:73], v[220:223], v[30:33]
	v_mfma_f32_16x16x32_bf16 v[22:25], v[82:85], v[220:223], v[22:25]
	v_mfma_f32_16x16x32_bf16 v[14:17], v[70:73], v[242:245], v[14:17]
	v_mfma_f32_16x16x32_bf16 v[6:9], v[82:85], v[242:245], v[6:9]
	s_setprio 0
	s_setprio 1
	v_mfma_f32_16x16x32_bf16 v[58:61], v[180:183], v[200:203], v[58:61]
	v_mfma_f32_16x16x32_bf16 v[50:53], v[190:193], v[200:203], v[50:53]
	v_mfma_f32_16x16x32_bf16 v[42:45], v[180:183], v[208:211], v[42:45]
	v_mfma_f32_16x16x32_bf16 v[34:37], v[190:193], v[208:211], v[34:37]
	v_mfma_f32_16x16x32_bf16 v[26:29], v[180:183], v[216:219], v[26:29]
	v_mfma_f32_16x16x32_bf16 v[18:21], v[190:193], v[216:219], v[18:21]
	v_mfma_f32_16x16x32_bf16 v[10:13], v[180:183], v[224:227], v[10:13]
	v_mfma_f32_16x16x32_bf16 v[2:5], v[190:193], v[224:227], v[2:5]
	v_mfma_f32_16x16x32_bf16 v[58:61], v[186:189], v[204:207], v[58:61]
	v_mfma_f32_16x16x32_bf16 v[50:53], v[196:199], v[204:207], v[50:53]
	v_mfma_f32_16x16x32_bf16 v[42:45], v[186:189], v[212:215], v[42:45]
	v_mfma_f32_16x16x32_bf16 v[34:37], v[196:199], v[212:215], v[34:37]
	v_mfma_f32_16x16x32_bf16 v[26:29], v[186:189], v[220:223], v[26:29]
	v_mfma_f32_16x16x32_bf16 v[18:21], v[196:199], v[220:223], v[18:21]
	v_mfma_f32_16x16x32_bf16 v[10:13], v[186:189], v[242:245], v[10:13]
	v_mfma_f32_16x16x32_bf16 v[2:5], v[196:199], v[242:245], v[2:5]
	s_setprio 0
	s_barrier
	s_add_i32 s76, s76, 2
	s_add_u32 s52, s52, 0x10000
	s_addc_u32 s53, s53, 0
	s_add_u32 s74, s74, 0x10000
	s_addc_u32 s75, s75, 0
	s_cmp_gt_u32 s76, 13
	s_cbranch_scc0 .LBB0_166
	s_and_b64 vcc, exec, s[8:9]
	s_cbranch_vccz .LBB0_169
	s_barrier

; #define PG8_STAGE(bufoff, gbase, voff) do { _Pragma("unroll") for (int _i = 0; _i < 2; ++_i) \
;         __builtin_amdgcn_global_load_lds((const unsigned*)((const char*)(gbase) + (voff)[_i]), (PG8_LAS unsigned*)(lds + (bufoff) + ldsw + _i * 8192), 16, 0, 0); } while (0)
; #define PG8_LDA(dst, b, h) do { _Pragma("unroll") for (int m = 0; m < 4; ++m) _Pragma("unroll") for (int k = 0; k < 2; ++k) dst[m][k] = *(const PG8_LAS bf16x8*)(lds + PG8_SA(b, h) + aoff + m * 2048 + k * 1024); } while (0)
; #define PG8_LDB(dst, b, h) do { _Pragma("unroll") for (int n = 0; n < 2; ++n) _Pragma("unroll") for (int k = 0; k < 2; ++k) dst[n][k] = *(const PG8_LAS bf16x8*)(lds + PG8_SB(b, h) + boff + n * 2048 + k * 1024); } while (0)
; #define PG8_MMA(ai, bj, At, Bt) do { __builtin_amdgcn_s_setprio(1); _Pragma("unroll") for (int m = 0; m < 4; ++m) _Pragma("unroll") for (int n = 0; n < 2; ++n) _Pragma("unroll") for (int k = 0; k < 2; ++k) \
;         acc[ai][bj][m][n] = __builtin_amdgcn_mfma_f32_16x16x32_bf16(Bt[n][k], At[m][k], acc[ai][bj][m][n], 0, 0, 0); __builtin_amdgcn_s_setprio(0); } while (0)
; #define PG8_WAIT_V(n) asm volatile("s_waitcnt vmcnt(" #n ")" ::: "memory")
; #define PG8_WAIT_L(n) asm volatile("s_waitcnt lgkmcnt(" #n ")" ::: "memory")
; #define PG8_BAR __builtin_amdgcn_s_barrier()
; #define PG8_SCHED __builtin_amdgcn_sched_barrier(0)
; template <class Epi, class Sched, bool ALIGN_EPI = false, bool SP2 = false, bool ATILED = false, bool BTILED = false>
; __device__ __forceinline__ void gemm_phase(PG8_LAS unsigned char* lds, const Gemm g, const Sched& S, const Epi& E, const int tid) {
;     ...
;             PG8_LDB(B0, 0, 0); PG8_LDB(B1, 0, 1); PG8_SCHED; PG8_LDA(At, 0, 0); PG8_STAGE(PG8_SA(1, 1), a1 + hstepA, voffA);
;             PG8_WAIT_V(8); PG8_WAIT_L(0); PG8_BAR; PG8_MMA(0, 0, At, B0); PG8_MMA(0, 1, At, B1); PG8_BAR; PG8_SCHED;
;             PG8_LDA(At, 0, 1); PG8_STAGE(PG8_SB(0, 0), b2, voffB); PG8_STAGE(PG8_SB(0, 1), b2 + hstepB, voffB); PG8_STAGE(PG8_SA(0, 0), a2, voffA);
;             PG8_WAIT_V(8); PG8_WAIT_L(0); PG8_BAR; PG8_MMA(1, 0, At, B0); PG8_MMA(1, 1, At, B1); PG8_BAR; PG8_SCHED;
.LBB0_553:
	s_add_u32 s26, s24, 0x4000
	s_addc_u32 s27, s25, 0
	s_cmp_eq_u32 s55, 12
	s_cselect_b32 s52, s5, s26
	s_cselect_b32 s53, s3, s27
	s_cselect_b32 s28, s17, s30
	s_cselect_b32 s29, s15, s54
	s_add_u32 s26, s52, 0x8000
	s_addc_u32 s27, s53, 0
	s_add_i32 s56, 0, 0x10000
	s_add_i32 s71, 0, 0x14000
	v_add_u32_e32 v78, s56, v242
	s_waitcnt vmcnt(0)
	v_add_u32_e32 v110, s71, v242
	ds_read_b128 v[66:69], v78
	ds_read_b128 v[70:73], v78 offset:1024
	ds_read_b128 v[74:77], v78 offset:2048
	ds_read_b128 v[78:81], v78 offset:3072
	ds_read_b128 v[82:85], v110
	ds_read_b128 v[86:89], v110 offset:1024
	ds_read_b128 v[106:109], v110 offset:2048
	ds_read_b128 v[110:113], v110 offset:3072
	v_lshl_add_u64 v[180:181], s[24:25], 0, v[198:199]
	s_add_i32 m0, s61, 0xc000
	ds_read_b128 v[130:133], v243
	ds_read_b128 v[134:137], v243 offset:1024
	ds_read_b128 v[146:149], v243 offset:2048
	ds_read_b128 v[158:161], v243 offset:3072
	ds_read_b128 v[202:205], v243 offset:4096
	ds_read_b128 v[206:209], v243 offset:5120
	ds_read_b128 v[210:213], v243 offset:6144
	ds_read_b128 v[214:217], v243 offset:7168
	global_load_lds_dwordx4 v[180:181], off
	v_lshl_add_u64 v[180:181], s[24:25], 0, v[200:201]
	s_add_i32 m0, s61, 0xe000
	s_nop 0
	global_load_lds_dwordx4 v[180:181], off
	s_waitcnt vmcnt(8)
	s_waitcnt lgkmcnt(0)
	s_barrier
	s_setprio 1
	s_waitcnt lgkmcnt(0)
	v_mfma_f32_16x16x32_bf16 v[174:177], v[66:69], v[130:133], v[174:177]
	v_mfma_f32_16x16x32_bf16 v[170:173], v[74:77], v[130:133], v[170:173]
	v_mfma_f32_16x16x32_bf16 v[154:157], v[66:69], v[146:149], v[154:157]
	v_mfma_f32_16x16x32_bf16 v[150:153], v[74:77], v[146:149], v[150:153]
	v_mfma_f32_16x16x32_bf16 v[126:129], v[66:69], v[202:205], v[126:129]
	v_mfma_f32_16x16x32_bf16 v[122:125], v[74:77], v[202:205], v[122:125]
	v_mfma_f32_16x16x32_bf16 v[102:105], v[66:69], v[210:213], v[102:105]
	v_mfma_f32_16x16x32_bf16 v[98:101], v[74:77], v[210:213], v[98:101]
	v_mfma_f32_16x16x32_bf16 v[174:177], v[70:73], v[134:137], v[174:177]
	v_mfma_f32_16x16x32_bf16 v[170:173], v[78:81], v[134:137], v[170:173]
	v_mfma_f32_16x16x32_bf16 v[154:157], v[70:73], v[158:161], v[154:157]
	v_mfma_f32_16x16x32_bf16 v[150:153], v[78:81], v[158:161], v[150:153]
	v_mfma_f32_16x16x32_bf16 v[126:129], v[70:73], v[206:209], v[126:129]
	v_mfma_f32_16x16x32_bf16 v[122:125], v[78:81], v[206:209], v[122:125]
	v_mfma_f32_16x16x32_bf16 v[102:105], v[70:73], v[214:217], v[102:105]
	v_mfma_f32_16x16x32_bf16 v[98:101], v[78:81], v[214:217], v[98:101]
	s_setprio 0
	s_setprio 1
	v_mfma_f32_16x16x32_bf16 v[166:169], v[82:85], v[130:133], v[166:169]
	v_mfma_f32_16x16x32_bf16 v[130:133], v[106:109], v[130:133], v[162:165]
	v_mfma_f32_16x16x32_bf16 v[138:141], v[106:109], v[146:149], v[138:141]
	v_mfma_f32_16x16x32_bf16 v[118:121], v[82:85], v[202:205], v[118:121]
	v_mfma_f32_16x16x32_bf16 v[114:117], v[106:109], v[202:205], v[114:117]
	v_mfma_f32_16x16x32_bf16 v[94:97], v[82:85], v[210:213], v[94:97]
	v_mfma_f32_16x16x32_bf16 v[90:93], v[106:109], v[210:213], v[90:93]
	v_mfma_f32_16x16x32_bf16 v[166:169], v[86:89], v[134:137], v[166:169]
	v_mfma_f32_16x16x32_bf16 v[130:133], v[110:113], v[134:137], v[130:133]
	v_mfma_f32_16x16x32_bf16 v[134:137], v[82:85], v[146:149], v[142:145]
	v_mfma_f32_16x16x32_bf16 v[138:141], v[110:113], v[158:161], v[138:141]
	v_mfma_f32_16x16x32_bf16 v[118:121], v[86:89], v[206:209], v[118:121]
	v_mfma_f32_16x16x32_bf16 v[114:117], v[110:113], v[206:209], v[114:117]
	v_mfma_f32_16x16x32_bf16 v[94:97], v[86:89], v[214:217], v[94:97]
	v_mfma_f32_16x16x32_bf16 v[90:93], v[110:113], v[214:217], v[90:93]
	v_mfma_f32_16x16x32_bf16 v[134:137], v[86:89], v[158:161], v[134:137]
	s_setprio 0
	s_barrier
	s_add_i32 s56, s56, s60
	v_lshl_add_u64 v[180:181], s[28:29], 0, v[188:189]
	s_mov_b32 m0, s56
	ds_read_b128 v[142:145], v243 offset:16384
	ds_read_b128 v[146:149], v243 offset:17408
	ds_read_b128 v[158:161], v243 offset:18432
	ds_read_b128 v[162:165], v243 offset:19456
	ds_read_b128 v[202:205], v243 offset:20480
	ds_read_b128 v[206:209], v243 offset:21504
	ds_read_b128 v[210:213], v243 offset:22528
	ds_read_b128 v[214:217], v243 offset:23552
	global_load_lds_dwordx4 v[180:181], off
	s_add_i32 m0, s56, 0x2000
	s_add_u32 s56, s28, 0x4000
	v_lshl_add_u64 v[180:181], s[28:29], 0, v[192:193]
	s_addc_u32 s57, s29, 0
	s_add_i32 s71, s71, s60
	global_load_lds_dwordx4 v[180:181], off
	v_lshl_add_u64 v[180:181], s[56:57], 0, v[188:189]
	s_mov_b32 m0, s71
	s_nop 0
	global_load_lds_dwordx4 v[180:181], off
	v_lshl_add_u64 v[180:181], s[56:57], 0, v[192:193]
	s_add_i32 m0, s71, 0x2000
	s_nop 0
	global_load_lds_dwordx4 v[180:181], off
	v_lshl_add_u64 v[180:181], s[52:53], 0, v[186:187]
	s_mov_b32 m0, s61
	s_nop 0
	global_load_lds_dwordx4 v[180:181], off
	v_lshl_add_u64 v[180:181], s[52:53], 0, v[190:191]
	s_mov_b32 m0, s62
	s_nop 0
	global_load_lds_dwordx4 v[180:181], off
	s_waitcnt vmcnt(8)
	s_waitcnt lgkmcnt(0)
	s_barrier
; #define PG8_STAGE(bufoff, gbase, voff) do { _Pragma("unroll") for (int _i = 0; _i < 2; ++_i) \
;         __builtin_amdgcn_global_load_lds((const unsigned*)((const char*)(gbase) + (voff)[_i]), (PG8_LAS unsigned*)(lds + (bufoff) + ldsw + _i * 8192), 16, 0, 0); } while (0)
; #define PG8_LDA(dst, b, h) do { _Pragma("unroll") for (int m = 0; m < 4; ++m) _Pragma("unroll") for (int k = 0; k < 2; ++k) dst[m][k] = *(const PG8_LAS bf16x8*)(lds + PG8_SA(b, h) + aoff + m * 2048 + k * 1024); } while (0)
; #define PG8_LDB(dst, b, h) do { _Pragma("unroll") for (int n = 0; n < 2; ++n) _Pragma("unroll") for (int k = 0; k < 2; ++k) dst[n][k] = *(const PG8_LAS bf16x8*)(lds + PG8_SB(b, h) + boff + n * 2048 + k * 1024); } while (0)
; #define PG8_MMA(ai, bj, At, Bt) do { __builtin_amdgcn_s_setprio(1); _Pragma("unroll") for (int m = 0; m < 4; ++m) _Pragma("unroll") for (int n = 0; n < 2; ++n) _Pragma("unroll") for (int k = 0; k < 2; ++k) \
;         acc[ai][bj][m][n] = __builtin_amdgcn_mfma_f32_16x16x32_bf16(Bt[n][k], At[m][k], acc[ai][bj][m][n], 0, 0, 0); __builtin_amdgcn_s_setprio(0); } while (0)
; #define PG8_WAIT_V(n) asm volatile("s_waitcnt vmcnt(" #n ")" ::: "memory")
; #define PG8_WAIT_L(n) asm volatile("s_waitcnt lgkmcnt(" #n ")" ::: "memory")
; #define PG8_BAR __builtin_amdgcn_s_barrier()
; #define PG8_SCHED __builtin_amdgcn_sched_barrier(0)
; template <class Epi, class Sched, bool ALIGN_EPI = false, bool SP2 = false, bool ATILED = false, bool BTILED = false>
; __device__ __forceinline__ void gemm_phase(PG8_LAS unsigned char* lds, const Gemm g, const Sched& S, const Epi& E, const int tid) {
;     ...
;             PG8_WAIT_V(8); PG8_WAIT_L(0); PG8_BAR; PG8_MMA(1, 0, At, B0); PG8_MMA(1, 1, At, B1); PG8_BAR; PG8_SCHED;
;             PG8_LDB(B0, 1, 0); PG8_LDB(B1, 1, 1); PG8_SCHED; PG8_LDA(At, 1, 0); PG8_STAGE(PG8_SA(0, 1), a2 + hstepA, voffA);
;             PG8_WAIT_V(8); PG8_WAIT_L(0); PG8_BAR; PG8_MMA(0, 0, At, B0); PG8_MMA(0, 1, At, B1); PG8_BAR; PG8_SCHED;
	s_setprio 1
	s_waitcnt lgkmcnt(0)
	v_mfma_f32_16x16x32_bf16 v[62:65], v[66:69], v[142:145], v[62:65]
	v_mfma_f32_16x16x32_bf16 v[58:61], v[74:77], v[142:145], v[58:61]
	v_mfma_f32_16x16x32_bf16 v[46:49], v[66:69], v[158:161], v[46:49]
	v_mfma_f32_16x16x32_bf16 v[42:45], v[74:77], v[158:161], v[42:45]
	v_mfma_f32_16x16x32_bf16 v[30:33], v[66:69], v[202:205], v[30:33]
	v_mfma_f32_16x16x32_bf16 v[26:29], v[74:77], v[202:205], v[26:29]
	v_mfma_f32_16x16x32_bf16 v[14:17], v[66:69], v[210:213], v[14:17]
	v_mfma_f32_16x16x32_bf16 v[10:13], v[74:77], v[210:213], v[10:13]
	v_mfma_f32_16x16x32_bf16 v[62:65], v[70:73], v[146:149], v[62:65]
	v_mfma_f32_16x16x32_bf16 v[58:61], v[78:81], v[146:149], v[58:61]
	v_mfma_f32_16x16x32_bf16 v[46:49], v[70:73], v[162:165], v[46:49]
	v_mfma_f32_16x16x32_bf16 v[42:45], v[78:81], v[162:165], v[42:45]
	v_mfma_f32_16x16x32_bf16 v[30:33], v[70:73], v[206:209], v[30:33]
	v_mfma_f32_16x16x32_bf16 v[26:29], v[78:81], v[206:209], v[26:29]
	v_mfma_f32_16x16x32_bf16 v[14:17], v[70:73], v[214:217], v[14:17]
	v_mfma_f32_16x16x32_bf16 v[10:13], v[78:81], v[214:217], v[10:13]
	s_setprio 0
	s_setprio 1
	v_mfma_f32_16x16x32_bf16 v[54:57], v[82:85], v[142:145], v[54:57]
	v_mfma_f32_16x16x32_bf16 v[50:53], v[106:109], v[142:145], v[50:53]
	v_mfma_f32_16x16x32_bf16 v[38:41], v[82:85], v[158:161], v[38:41]
	v_mfma_f32_16x16x32_bf16 v[34:37], v[106:109], v[158:161], v[34:37]
	v_mfma_f32_16x16x32_bf16 v[22:25], v[82:85], v[202:205], v[22:25]
	v_mfma_f32_16x16x32_bf16 v[18:21], v[106:109], v[202:205], v[18:21]
	v_mfma_f32_16x16x32_bf16 v[6:9], v[82:85], v[210:213], v[6:9]
	v_mfma_f32_16x16x32_bf16 v[2:5], v[106:109], v[210:213], v[2:5]
	v_mfma_f32_16x16x32_bf16 v[54:57], v[86:89], v[146:149], v[54:57]
	v_mfma_f32_16x16x32_bf16 v[50:53], v[110:113], v[146:149], v[50:53]
	v_mfma_f32_16x16x32_bf16 v[38:41], v[86:89], v[162:165], v[38:41]
	v_mfma_f32_16x16x32_bf16 v[34:37], v[110:113], v[162:165], v[34:37]
	v_mfma_f32_16x16x32_bf16 v[22:25], v[86:89], v[206:209], v[22:25]
	v_mfma_f32_16x16x32_bf16 v[18:21], v[110:113], v[206:209], v[18:21]
	v_mfma_f32_16x16x32_bf16 v[6:9], v[86:89], v[214:217], v[6:9]
	v_mfma_f32_16x16x32_bf16 v[2:5], v[110:113], v[214:217], v[2:5]
	s_setprio 0
	s_barrier
	s_add_i32 s56, 0, 0x18000
	s_add_i32 s57, 0, 0x1c000
	v_add_u32_e32 v78, s56, v242
	v_add_u32_e32 v110, s57, v242
	ds_read_b128 v[66:69], v78
	ds_read_b128 v[70:73], v78 offset:1024
	ds_read_b128 v[74:77], v78 offset:2048
	ds_read_b128 v[78:81], v78 offset:3072
	ds_read_b128 v[82:85], v110
	ds_read_b128 v[86:89], v110 offset:1024
	ds_read_b128 v[106:109], v110 offset:2048
	ds_read_b128 v[110:113], v110 offset:3072
	s_add_u32 s52, s52, 0x4000
	s_addc_u32 s53, s53, 0
	s_mov_b32 m0, s63
	v_lshl_add_u64 v[162:163], s[52:53], 0, v[186:187]
	ds_read_b128 v[142:145], v243 offset:32768
	ds_read_b128 v[146:149], v243 offset:33792
	ds_read_b128 v[158:161], v243 offset:34816
	ds_read_b128 v[202:205], v243 offset:35840
	ds_read_b128 v[206:209], v243 offset:36864
	ds_read_b128 v[210:213], v243 offset:37888
	ds_read_b128 v[214:217], v243 offset:38912
	ds_read_b128 v[218:221], v243 offset:39936
	global_load_lds_dwordx4 v[162:163], off
	v_lshl_add_u64 v[162:163], s[52:53], 0, v[190:191]
	s_mov_b32 m0, s64
	s_nop 0
	global_load_lds_dwordx4 v[162:163], off
	s_waitcnt vmcnt(8)
	s_waitcnt lgkmcnt(0)
	s_barrier
	s_setprio 1
	s_waitcnt lgkmcnt(0)
	v_mfma_f32_16x16x32_bf16 v[162:165], v[66:69], v[142:145], v[174:177]
	v_mfma_f32_16x16x32_bf16 v[174:177], v[70:73], v[146:149], v[162:165]
	v_mfma_f32_16x16x32_bf16 v[162:165], v[74:77], v[142:145], v[170:173]
	v_mfma_f32_16x16x32_bf16 v[154:157], v[66:69], v[158:161], v[154:157]
	v_mfma_f32_16x16x32_bf16 v[150:153], v[74:77], v[158:161], v[150:153]
	v_mfma_f32_16x16x32_bf16 v[126:129], v[66:69], v[206:209], v[126:129]
	v_mfma_f32_16x16x32_bf16 v[122:125], v[74:77], v[206:209], v[122:125]
	v_mfma_f32_16x16x32_bf16 v[102:105], v[66:69], v[214:217], v[102:105]
	v_mfma_f32_16x16x32_bf16 v[98:101], v[74:77], v[214:217], v[98:101]
	v_mfma_f32_16x16x32_bf16 v[170:173], v[78:81], v[146:149], v[162:165]
	v_mfma_f32_16x16x32_bf16 v[154:157], v[70:73], v[202:205], v[154:157]
	v_mfma_f32_16x16x32_bf16 v[150:153], v[78:81], v[202:205], v[150:153]
	v_mfma_f32_16x16x32_bf16 v[126:129], v[70:73], v[210:213], v[126:129]
	v_mfma_f32_16x16x32_bf16 v[122:125], v[78:81], v[210:213], v[122:125]
	v_mfma_f32_16x16x32_bf16 v[102:105], v[70:73], v[218:221], v[102:105]
	v_mfma_f32_16x16x32_bf16 v[98:101], v[78:81], v[218:221], v[98:101]
	s_setprio 0
	s_setprio 1
	v_mfma_f32_16x16x32_bf16 v[162:165], v[82:85], v[142:145], v[166:169]
	v_mfma_f32_16x16x32_bf16 v[130:133], v[106:109], v[142:145], v[130:133]
	v_mfma_f32_16x16x32_bf16 v[166:169], v[86:89], v[146:149], v[162:165]
	v_mfma_f32_16x16x32_bf16 v[162:165], v[110:113], v[146:149], v[130:133]
	v_mfma_f32_16x16x32_bf16 v[130:133], v[82:85], v[158:161], v[134:137]
	v_mfma_f32_16x16x32_bf16 v[142:145], v[86:89], v[202:205], v[130:133]
	v_mfma_f32_16x16x32_bf16 v[130:133], v[106:109], v[158:161], v[138:141]
	v_mfma_f32_16x16x32_bf16 v[118:121], v[82:85], v[206:209], v[118:121]
	v_mfma_f32_16x16x32_bf16 v[114:117], v[106:109], v[206:209], v[114:117]
	v_mfma_f32_16x16x32_bf16 v[94:97], v[82:85], v[214:217], v[94:97]
	v_mfma_f32_16x16x32_bf16 v[90:93], v[106:109], v[214:217], v[90:93]
	v_mfma_f32_16x16x32_bf16 v[138:141], v[110:113], v[202:205], v[130:133]
	v_mfma_f32_16x16x32_bf16 v[118:121], v[86:89], v[210:213], v[118:121]
	v_mfma_f32_16x16x32_bf16 v[114:117], v[110:113], v[210:213], v[114:117]
	v_mfma_f32_16x16x32_bf16 v[94:97], v[86:89], v[218:221], v[94:97]
	v_mfma_f32_16x16x32_bf16 v[90:93], v[110:113], v[218:221], v[90:93]
	s_setprio 0
	s_barrier
; #define PG8_STAGE(bufoff, gbase, voff) do { _Pragma("unroll") for (int _i = 0; _i < 2; ++_i) \
;         __builtin_amdgcn_global_load_lds((const unsigned*)((const char*)(gbase) + (voff)[_i]), (PG8_LAS unsigned*)(lds + (bufoff) + ldsw + _i * 8192), 16, 0, 0); } while (0)
; #define PG8_LDA(dst, b, h) do { _Pragma("unroll") for (int m = 0; m < 4; ++m) _Pragma("unroll") for (int k = 0; k < 2; ++k) dst[m][k] = *(const PG8_LAS bf16x8*)(lds + PG8_SA(b, h) + aoff + m * 2048 + k * 1024); } while (0)
; #define PG8_MMA(ai, bj, At, Bt) do { __builtin_amdgcn_s_setprio(1); _Pragma("unroll") for (int m = 0; m < 4; ++m) _Pragma("unroll") for (int n = 0; n < 2; ++n) _Pragma("unroll") for (int k = 0; k < 2; ++k) \
;         acc[ai][bj][m][n] = __builtin_amdgcn_mfma_f32_16x16x32_bf16(Bt[n][k], At[m][k], acc[ai][bj][m][n], 0, 0, 0); __builtin_amdgcn_s_setprio(0); } while (0)
; #define PG8_WAIT_V(n) asm volatile("s_waitcnt vmcnt(" #n ")" ::: "memory")
; #define PG8_WAIT_L(n) asm volatile("s_waitcnt lgkmcnt(" #n ")" ::: "memory")
; #define PG8_BAR __builtin_amdgcn_s_barrier()
; #define PG8_SCHED __builtin_amdgcn_sched_barrier(0)
; template <class Epi, class Sched, bool ALIGN_EPI = false, bool SP2 = false, bool ATILED = false, bool BTILED = false>
; __device__ __forceinline__ void gemm_phase(PG8_LAS unsigned char* lds, const Gemm g, const Sched& S, const Epi& E, const int tid) {
;     ...
;             PG8_LDA(At, 1, 1); PG8_STAGE(PG8_SB(1, 0), b3, voffB); PG8_STAGE(PG8_SB(1, 1), b3 + hstepB, voffB); PG8_STAGE(PG8_SA(1, 0), a3, voffA);
;             PG8_WAIT_V(8); PG8_WAIT_L(0); PG8_BAR; PG8_MMA(1, 0, At, B0); PG8_MMA(1, 1, At, B1); PG8_BAR; PG8_SCHED;
;     __device__ __forceinline__ void operator()(const f32x4 (&acc)[2][2][4][2], const pg8::Unit& u, int wr, int wc, int fr, int fq) const {
;         const int slot = 4 * u.pn + wc;
;         if (slot >= 46) return;
	s_add_u32 s52, s28, 0x8000
	s_addc_u32 s53, s29, 0
	s_add_i32 s56, s56, s60
	v_lshl_add_u64 v[180:181], s[52:53], 0, v[188:189]
	s_mov_b32 m0, s56
	ds_read_b128 v[130:133], v243 offset:49152
	ds_read_b128 v[134:137], v243 offset:50176
	ds_read_b128 v[146:149], v243 offset:51200
	ds_read_b128 v[158:161], v243 offset:52224
	ds_read_b128 v[202:205], v243 offset:53248
	ds_read_b128 v[206:209], v243 offset:54272
	ds_read_b128 v[210:213], v243 offset:55296
	ds_read_b128 v[214:217], v243 offset:56320
	global_load_lds_dwordx4 v[180:181], off
	s_add_i32 m0, s56, 0x2000
	s_add_u32 s28, s28, 0xc000
	v_lshl_add_u64 v[180:181], s[52:53], 0, v[192:193]
	s_addc_u32 s29, s29, 0
	s_add_i32 s52, s57, s60
	global_load_lds_dwordx4 v[180:181], off
	v_lshl_add_u64 v[180:181], s[28:29], 0, v[188:189]
	s_mov_b32 m0, s52
	s_nop 0
	global_load_lds_dwordx4 v[180:181], off
	v_lshl_add_u64 v[180:181], s[28:29], 0, v[192:193]
	s_add_i32 m0, s52, 0x2000
	s_nop 0
	global_load_lds_dwordx4 v[180:181], off
	v_lshl_add_u64 v[180:181], s[26:27], 0, v[186:187]
	s_mov_b32 m0, s66
	s_nop 0
	global_load_lds_dwordx4 v[180:181], off
	v_lshl_add_u64 v[180:181], s[26:27], 0, v[190:191]
	s_mov_b32 m0, s67
	s_nop 0
	global_load_lds_dwordx4 v[180:181], off
	s_waitcnt vmcnt(8)
	s_cmp_lg_u32 s55, 12
	s_cbranch_scc1 .Linp_touch_skip
	v_lshl_add_u32 v253, s4, 8, v1
	v_lshlrev_b32_e32 v253, 2, v253
	global_load_dword v252, v253, s[8:9]
	global_load_dword v252, v253, s[8:9] offset:128
	global_load_dword v252, v253, s[8:9] offset:512
	global_load_dword v252, v253, s[8:9] offset:640
.Linp_touch_skip:
	s_waitcnt lgkmcnt(0)
	s_barrier
	s_setprio 1
	s_waitcnt lgkmcnt(0)
	v_mfma_f32_16x16x32_bf16 v[62:65], v[66:69], v[130:133], v[62:65]
	v_mfma_f32_16x16x32_bf16 v[58:61], v[74:77], v[130:133], v[58:61]
	v_mfma_f32_16x16x32_bf16 v[46:49], v[66:69], v[146:149], v[46:49]
	v_mfma_f32_16x16x32_bf16 v[42:45], v[74:77], v[146:149], v[42:45]
	v_mfma_f32_16x16x32_bf16 v[30:33], v[66:69], v[202:205], v[30:33]
	v_mfma_f32_16x16x32_bf16 v[26:29], v[74:77], v[202:205], v[26:29]
	v_mfma_f32_16x16x32_bf16 v[14:17], v[66:69], v[210:213], v[14:17]
	v_mfma_f32_16x16x32_bf16 v[10:13], v[74:77], v[210:213], v[10:13]
	v_mfma_f32_16x16x32_bf16 v[62:65], v[70:73], v[134:137], v[62:65]
	v_mfma_f32_16x16x32_bf16 v[58:61], v[78:81], v[134:137], v[58:61]
	v_mfma_f32_16x16x32_bf16 v[46:49], v[70:73], v[158:161], v[46:49]
	v_mfma_f32_16x16x32_bf16 v[42:45], v[78:81], v[158:161], v[42:45]
	v_mfma_f32_16x16x32_bf16 v[30:33], v[70:73], v[206:209], v[30:33]
	v_mfma_f32_16x16x32_bf16 v[26:29], v[78:81], v[206:209], v[26:29]
	v_mfma_f32_16x16x32_bf16 v[14:17], v[70:73], v[214:217], v[14:17]
	v_mfma_f32_16x16x32_bf16 v[10:13], v[78:81], v[214:217], v[10:13]
	s_setprio 0
	s_setprio 1
	v_mfma_f32_16x16x32_bf16 v[54:57], v[82:85], v[130:133], v[54:57]
	v_mfma_f32_16x16x32_bf16 v[50:53], v[106:109], v[130:133], v[50:53]
	v_mfma_f32_16x16x32_bf16 v[38:41], v[82:85], v[146:149], v[38:41]
	v_mfma_f32_16x16x32_bf16 v[34:37], v[106:109], v[146:149], v[34:37]
	v_mfma_f32_16x16x32_bf16 v[22:25], v[82:85], v[202:205], v[22:25]
	v_mfma_f32_16x16x32_bf16 v[18:21], v[106:109], v[202:205], v[18:21]
	v_mfma_f32_16x16x32_bf16 v[6:9], v[82:85], v[210:213], v[6:9]
	v_mfma_f32_16x16x32_bf16 v[2:5], v[106:109], v[210:213], v[2:5]
	v_mfma_f32_16x16x32_bf16 v[54:57], v[86:89], v[134:137], v[54:57]
	v_mfma_f32_16x16x32_bf16 v[50:53], v[110:113], v[134:137], v[50:53]
	v_mfma_f32_16x16x32_bf16 v[38:41], v[86:89], v[158:161], v[38:41]
	v_mfma_f32_16x16x32_bf16 v[34:37], v[110:113], v[158:161], v[34:37]
	v_mfma_f32_16x16x32_bf16 v[22:25], v[86:89], v[206:209], v[22:25]
	v_mfma_f32_16x16x32_bf16 v[18:21], v[110:113], v[206:209], v[18:21]
	v_mfma_f32_16x16x32_bf16 v[6:9], v[86:89], v[214:217], v[6:9]
	v_mfma_f32_16x16x32_bf16 v[2:5], v[110:113], v[214:217], v[2:5]
	s_setprio 0
	s_barrier
	s_add_i32 s55, s55, 2
	s_add_u32 s24, s24, 0x10000
	s_addc_u32 s25, s25, 0
	s_add_u32 s30, s30, 0x10000
	s_addc_u32 s54, s54, 0
	s_cmp_gt_u32 s55, 13
	s_cbranch_scc0 .LBB0_553
	s_and_b64 vcc, exec, s[10:11]
	s_cbranch_vccz .LBB0_557
	s_barrier
	s_lshl_b32 s3, s2, 2
	s_or_b32 s24, s3, s65
	s_cmp_gt_i32 s24, 45
	s_cbranch_scc0 .LBB0_558
